# plus diff loop: 3-barrier syncthreads_and replaced by 1-barrier LDS counter vote
# speedup vs baseline: 1.0105x; 1.0100x over previous
; __device__ __forceinline__ unsigned cvt_pk_bf16(float lo, float hi) { f32x2_cv v = {lo, hi}; bf16x2_cv b = __builtin_convertvector(v, bf16x2_cv); return __builtin_bit_cast(unsigned, b); }
; __device__ __forceinline__ float bf_lo(unsigned u) { return __uint_as_float(u << 16); }
; #define ATT_LOAD(t) do { vreg = *(const GAS u32x4*)(vsrc + (unsigned)((t) * 64)); kreg = *(const GAS u32x4*)(ksrc + (unsigned)((t) * 64 * kpitch)); \
;         if (MODE == 0) { if (tid < 256) krreg = *(const GAS u32x4*)(krsrc + (unsigned)((t) * 64 * 32)); } \
;         else { if (tid < 64) pkreg = (float)posg[(t) * 64 + tid]; } } while (0)
;     ...
;     float m[NM];
;     f32x16 negm, lsum;
; #pragma unroll
;     for (int r = 0; r < 16; ++r) { negm[r] = 0.f; lsum[r] = 0.f; }
; #pragma unroll
;     for (int i = 0; i < NM; ++i) { m[i] = 0.f; l[i] = (MODE == 0) ? 1.0f : 0.f;
; #pragma unroll
;         for (int r = 0; r < 16; ++r) { o[i][0][r] = 0.f; o[i][1][r] = 0.f; } }
;     bf16x8 qx[2];
;     if constexpr (MODE == 1 && FAST) { unsigned s1, s2, s3; split3_bf16(slope2, s1, s2, s3);
;         const unsigned e1 = cvt_pk_bf16(bf_lo(s1) * 64.0f, bf_lo(s2) * 64.0f), e2 = (cvt_pk_bf16(bf_lo(s3) * 64.0f, 0.f) & 0xffffu) | (s1 << 16), e3 = s2 | (s3 << 16);
;         const u32x4 qv = {hi ? 0u : e1, hi ? 0u : e2, hi ? 0u : e3, 0u}; qx[0] = __builtin_bit_cast(bf16x8, qv); qx[1] = qx[0]; }
;     ATT_LOAD(REV ? NT - 1 : 0); ATT_STORE(0); __syncthreads();
; template <int MODE, bool FAST = false> __device__ __forceinline__ void attn_unit(LAS unsigned char* lds, const P& A, int b, int h, int qb) {
;     ...
;             float k0 = 0.f, k1 = 0.f; const float* km = A.kmax + (b * 16 + h * 2);
;             for (int blk = lane; blk < A.nblk; blk += 64) { k0 = fmaxf(k0, km[blk * 32]); k1 = fmaxf(k1, km[blk * 32 + 1]); }
; #pragma unroll
;             for (int sft = 1; sft < 64; sft <<= 1) { k0 = fmaxf(k0, __shfl_xor(k0, sft)); k1 = fmaxf(k1, __shfl_xor(k1, sft)); }
;             bq0 = 1.02f * sqrtf(n0 * k0) + 0.05f; bq1 = 1.02f * sqrtf(n1 * k1) + 0.05f;
.LBB0_165:
	s_or_b64 exec, exec, s[46:47]
	s_add_i32 s26, s69, 1
	v_cvt_f32_ubyte0_e32 v5, s26
	v_exp_f32_e64 v5, -v5
	s_movk_i32 s26, 0x90
	v_lshlrev_b32_e32 v210, 4, v4
	v_mul_lo_u32 v209, v1, s26
	v_mul_f32_e32 v211, 0x3fb8aa3b, v5
	v_cvt_pk_bf16_f32 v4, v211, 0
	v_lshlrev_b32_e32 v4, 16, v4
	s_mov_b32 s26, 0x3fb8aa3b
	v_fma_f32 v19, v5, s26, -v4
	v_cvt_pk_bf16_f32 v18, v19, 0
	v_add_u32_e32 v13, 0x100, v209
	v_lshlrev_b32_e32 v5, 16, v18
	s_mov_b32 s26, 0x42800000
	v_pk_mul_f32 v[6:7], v[4:5], s[26:27] op_sel_hi:[1,0]
	v_add_u32_e32 v20, v13, v210
	v_lshlrev_b32_e32 v225, 2, v0
	s_waitcnt vmcnt(0)
	ds_write_b128 v20, v[164:167]
	s_and_saveexec_b64 s[46:47], s[44:45]
	v_add_u32_e32 v20, 0x100, v225
	ds_write_b32 v20, v197 offset:17920
	s_or_b64 exec, exec, s[46:47]
	v_sub_f32_e32 v5, v19, v5
	v_cvt_pk_bf16_f32 v5, v5, 0
	v_lshlrev_b32_e32 v5, 16, v5
	v_cvt_pk_bf16_f32 v6, v6, v7
	v_mul_f32_e32 v7, 0x42800000, v5
	v_cvt_pk_bf16_f32 v7, v7, 0
	v_or_b32_sdwa v4, v7, v4 dst_sel:DWORD dst_unused:UNUSED_PAD src0_sel:WORD_0 src1_sel:DWORD
	v_cndmask_b32_e64 v168, 0, v6, s[50:51]
	s_waitcnt lgkmcnt(2)
	v_max_f32_e32 v6, v17, v17
	v_max_f32_e32 v7, v16, v16
	v_cndmask_b32_e64 v169, 0, v4, s[50:51]
	v_add_f32_e32 v4, v9, v11
	v_max_f32_e32 v6, v7, v6
	v_mul_f32_e32 v4, v4, v6
	s_mov_b32 s26, 0xf800000
	v_mul_f32_e32 v6, 0x4f800000, v4
	v_cmp_gt_f32_e32 vcc, s26, v4
	s_waitcnt lgkmcnt(1)
	v_max_f32_e32 v7, v15, v15
	v_max_f32_e32 v9, v14, v14
	v_cndmask_b32_e32 v4, v4, v6, vcc
	v_sqrt_f32_e32 v6, v4
	v_or_b32_sdwa v5, v5, v18 dst_sel:DWORD dst_unused:UNUSED_PAD src0_sel:DWORD src1_sel:WORD_0
	v_max_f32_e32 v7, v9, v7
	v_cndmask_b32_e64 v170, 0, v5, s[50:51]
	v_add_u32_e32 v9, -1, v6
	v_add_f32_e32 v5, v10, v12
	v_fma_f32 v10, -v9, v6, v4
	v_cmp_ge_f32_e64 s[46:47], 0, v10
	v_add_u32_e32 v10, 1, v6
	v_mul_f32_e32 v5, v5, v7
	v_cndmask_b32_e64 v9, v6, v9, s[46:47]
	v_fma_f32 v6, -v10, v6, v4
	v_cmp_lt_f32_e64 s[46:47], 0, v6
	v_mul_f32_e32 v7, 0x4f800000, v5
	s_lshl_b32 s20, s20, 7
	v_cndmask_b32_e64 v6, v9, v10, s[46:47]
	v_mul_f32_e32 v9, 0x37800000, v6
	v_cndmask_b32_e32 v6, v6, v9, vcc
	v_cmp_gt_f32_e32 vcc, s26, v5
	v_mov_b32_e32 v9, 0x260
	v_cmp_class_f32_e64 s[46:47], v4, v9
	v_cndmask_b32_e32 v5, v5, v7, vcc
	v_sqrt_f32_e32 v7, v5
	v_cndmask_b32_e64 v4, v6, v4, s[46:47]
	v_mov_b32_e32 v10, 0x3d4ccccd
	v_fmamk_f32 v226, v4, 0x3f828f5c, v10
	v_add_u32_e32 v4, -1, v7
	v_fma_f32 v6, -v4, v7, v5
	s_ashr_i32 s26, s25, 31
	v_cmp_ge_f32_e64 s[46:47], 0, v6
	v_add_u32_e32 v6, 1, v7
	s_lshr_b32 s26, s26, 26
	v_cndmask_b32_e64 v4, v7, v4, s[46:47]
	v_fma_f32 v7, -v6, v7, v5
	s_add_i32 s25, s25, s26
	s_movk_i32 s26, 0x88
	v_cmp_lt_f32_e64 s[46:47], 0, v7
	v_mul_lo_u32 v229, v1, s26
	v_lshlrev_b32_e32 v1, 3, v1
	v_cndmask_b32_e64 v4, v4, v6, s[46:47]
	v_sub_u32_e32 v1, v13, v1
	s_movk_i32 s26, 0x2400
	v_mul_f32_e32 v6, 0x37800000, v4
	s_ashr_i32 s25, s25, 6
	s_lshl_b32 s28, s97, 2
	v_add3_u32 v1, v1, v210, s26
	s_and_b32 s20, s20, 0x8000
	s_lshl_b32 s26, s97, 10
	v_cndmask_b32_e32 v4, v4, v6, vcc
	v_cmp_class_f32_e32 vcc, v5, v9
	s_sub_i32 s29, s25, s28
	s_add_i32 s30, s12, 0x80
	s_or_b32 s20, s20, s26
	v_readlane_b32 s26, v255, 24
	v_cndmask_b32_e32 v4, v4, v5, vcc
	ds_write2_b64 v1, v[160:161], v[162:163] offset1:1
	v_lshlrev_b32_e32 v1, 2, v2
	s_add_u32 s26, s26, s20
	v_readlane_b32 s20, v255, 25
	v_fmamk_f32 v227, v4, 0x3f828f5c, v10
	v_and_b32_e32 v4, 31, v0
	v_sub_u32_e32 v234, v8, v1
	v_ashrrev_i32_e32 v1, 31, v0
	s_addc_u32 s27, s20, 0
	s_lshl_b32 s20, s97, 18
	v_mov_b32_e32 v14, v3
	v_mov_b32_e32 v15, v3
	v_mul_u32_u24_e32 v230, 0x90, v4
	v_lshlrev_b32_e32 v231, 4, v2
	v_mul_u32_u24_e32 v232, 0x88, v4
	v_lshlrev_b32_e32 v233, 3, v2
	v_mul_i32_i24_e32 v235, 0xffffff74, v4
	v_lshl_add_u64 v[202:203], v[0:1], 2, s[26:27]
	s_bitset1_b32 s20, 17
	v_mov_b32_e32 v0, v3
	v_mov_b32_e32 v1, v3
	v_mov_b32_e32 v2, v3
	v_mov_b32_e32 v4, v3
	v_mov_b32_e32 v5, v3
	v_mov_b32_e32 v6, v3
	v_mov_b32_e32 v7, v3
	v_mov_b32_e32 v8, v3
	v_mov_b32_e32 v9, v3
	v_mov_b32_e32 v10, v3
	v_mov_b32_e32 v11, v3
	v_mov_b32_e32 v12, v3
	v_mov_b32_e32 v13, v3
	v_mov_b64_e32 v[62:63], v[14:15]
	v_mov_b64_e32 v[30:31], v[14:15]
	v_mov_b64_e32 v[78:79], v[14:15]
	v_mov_b64_e32 v[46:47], v[14:15]
	s_mov_b32 s48, 0
	s_sub_i32 s26, 0, s28
	s_add_i32 s27, s29, -3
	v_mov_b32_e32 v228, 0
	v_mov_b32_e32 v206, s20
	v_mov_b32_e32 v204, s30
	v_mov_b32_e32 v80, 0
	v_mov_b32_e32 v171, 0
	v_mov_b32_e32 v175, 0
	v_mov_b64_e32 v[60:61], v[12:13]
	v_mov_b64_e32 v[58:59], v[10:11]
	v_mov_b64_e32 v[56:57], v[8:9]
	v_mov_b64_e32 v[54:55], v[6:7]
	v_mov_b64_e32 v[52:53], v[4:5]
	v_mov_b64_e32 v[50:51], v[2:3]
	v_mov_b64_e32 v[48:49], v[0:1]
	v_mov_b64_e32 v[28:29], v[12:13]
	v_mov_b64_e32 v[26:27], v[10:11]
	v_mov_b64_e32 v[24:25], v[8:9]
	v_mov_b64_e32 v[22:23], v[6:7]
	v_mov_b64_e32 v[20:21], v[4:5]
	v_mov_b64_e32 v[18:19], v[2:3]
	v_mov_b64_e32 v[16:17], v[0:1]
	v_mov_b64_e32 v[76:77], v[12:13]
	v_mov_b64_e32 v[74:75], v[10:11]
	v_mov_b64_e32 v[72:73], v[8:9]
	v_mov_b64_e32 v[70:71], v[6:7]
	v_mov_b64_e32 v[68:69], v[4:5]
	v_mov_b64_e32 v[66:67], v[2:3]
	v_mov_b64_e32 v[64:65], v[0:1]
	v_mov_b64_e32 v[44:45], v[12:13]
	v_mov_b64_e32 v[42:43], v[10:11]
	v_mov_b64_e32 v[40:41], v[8:9]
	v_mov_b64_e32 v[38:39], v[6:7]
	v_mov_b64_e32 v[36:37], v[4:5]
	v_mov_b64_e32 v[34:35], v[2:3]
	v_mov_b64_e32 v[32:33], v[0:1]
	v_mov_b32_e32 v236, 0
	s_mov_b64 s[46:47], exec
	s_mov_b64 exec, 1
	ds_write_b32 v236, v236 offset:16
	ds_write_b32 v236, v236 offset:20
	ds_write_b32 v236, v236 offset:24
	s_mov_b64 exec, s[46:47]
	s_mov_b32 s101, 16
	v_mov_b32_e32 v237, 0
	v_mov_b32_e32 v238, 0
	v_mov_b32_e32 v172, v168
	v_mov_b32_e32 v173, v169
	v_mov_b32_e32 v174, v170
	s_waitcnt lgkmcnt(0)
	s_barrier

;     ...
;             if (__syncthreads_and(wdone)) break;
.LBB0_205:
	s_add_u32 s99, s101, 4
	s_cmp_gt_u32 s99, 24
	s_cselect_b32 s99, 16, s99
	v_mov_b32_e32 v1, s101
	v_mov_b32_e32 v2, s99
	s_mov_b64 s[46:47], exec
	s_mov_b64 exec, 1
	ds_add_u32 v1, v80
	ds_write_b32 v2, v3
	s_mov_b64 exec, s[46:47]
	s_mov_b32 s101, s99
	s_waitcnt lgkmcnt(0)
	s_barrier
	ds_read_b32 v0, v1
	s_waitcnt lgkmcnt(0)
	v_cmp_eq_u32_e32 vcc, 8, v0
	s_nop 1
	v_cndmask_b32_e64 v0, 0, 1, vcc
